# v18 + P2 idle half-round runs two passes (3072 w_ffn_out items, then w_o moved out of P0); P17 idle round converts w_ffn_out from item 3072 (37 items per wave, deepened loop)
# baseline (speedup 1.0000x reference)
; __device__ __forceinline__ int lane_id() { int l; asm volatile("v_mbcnt_lo_u32_b32 %0, -1, 0\n\tv_mbcnt_hi_u32_b32 %0, -1, %0" : "=v"(l)); return l; }
; #define CONV_WFO(lo_, hi_, w_, nw_) do { LAS float* scr_ = (LAS float*)(lds + wave * 16384); for (int r = (lo_) + (w_); r < (hi_); r += (nw_)) { const int nblk = 4096 / 32, kb = r / nblk, nb = r % nblk; \
;         p0_item(in_w_ffn_out, 4096, DFF, Wfo_t, nb * 32, nb * 32, kb * 64, nullptr, scr_, lane); } } while (0)
; __global__ void __launch_bounds__(NWAVES * 64, 2) mk_fwd(Args args) {
;     ...
;         { const int lane = lane_id(); if (split && bx >= 128) { CONV_WFO(0, I_FO_P2, (bx - 128) * NWAVES + wave, 128 * NWAVES); __syncthreads(); } }
.LBB0_355:
	v_readlane_b32 s6, v237, 53
	s_cmpk_lt_i32 s84, 0x80
	v_readlane_b32 s7, v237, 54
	s_cselect_b64 s[4:5], -1, 0
	s_xor_b64 s[6:7], s[6:7], -1
	s_or_b64 s[4:5], s[4:5], s[6:7]
	s_and_b64 vcc, exec, s[4:5]
	v_mbcnt_lo_u32_b32 v2, -1, 0
	v_mbcnt_hi_u32_b32 v2, -1, v2
	s_cbranch_vccnz .LBB0_366
	s_lshl_b32 s4, s84, 3
	s_add_i32 s4, s93, s4
	s_add_i32 s10, s4, 0xfffffc00
	s_cmpk_gt_i32 s10, 0x1bff
	s_cbranch_scc1 .LBB0_365
	v_and_b32_e32 v0, 7, v2
	v_lshlrev_b32_e32 v4, 4, v0
	s_waitcnt lgkmcnt(0)
	v_mov_b32_e32 v5, 0
	s_lshl_b32 s4, s93, 14
	v_ashrrev_i32_e32 v21, 3, v2
	v_mul_u32_u24_e32 v3, 0x420, v0
	v_lshl_add_u64 v[0:1], s[78:79], 0, v[4:5]
	s_mov_b64 s[6:7], 0x15b00000
	s_add_i32 s8, s4, 0
	v_ashrrev_i32_e32 v20, 5, v2
	v_lshl_add_u64 v[0:1], v[0:1], 0, s[6:7]
	v_lshlrev_b32_e32 v4, 2, v21
	s_movk_i32 s6, 0x84
	v_add3_u32 v22, s8, v3, v4
	v_mul_lo_u32 v3, v20, s6
	v_lshlrev_b32_e32 v2, 2, v2
	v_readlane_b32 s24, v236, 6
	v_add_u32_e32 v3, s4, v3
	v_and_b32_e32 v4, 0x7c, v2
	v_readlane_b32 s26, v236, 8
	v_readlane_b32 s27, v236, 9
	s_mov_b32 s5, 0
	v_add3_u32 v23, v3, v4, 0
	v_lshl_add_u64 v[2:3], s[26:27], 0, v[4:5]
	v_add_u32_e32 v24, 14, v20
	v_add_u32_e32 v25, 12, v20
	v_add_u32_e32 v26, 10, v20
	v_add_u32_e32 v27, 8, v20
	v_add_u32_e32 v28, 6, v20
	v_add_u32_e32 v29, 4, v20
	v_add_u32_e32 v30, 2, v20
	s_movk_i32 s11, 0x5600
	v_readlane_b32 s25, v236, 7
	v_readlane_b32 s28, v236, 10
	v_readlane_b32 s29, v236, 11
	v_readlane_b32 s30, v236, 12
	v_readlane_b32 s31, v236, 13
	s_movk_i32 s4, 0xc00
	v_writelane_b32 v236, s4, 60
	s_branch .LBB0_359
.LBB0_358:
	s_add_i32 s10, s10, 0x400
	v_readlane_b32 s4, v236, 60
	s_cmp_lt_i32 s10, s4
	s_cbranch_scc1 .LBB0_359
	s_cmpk_eq_i32 s4, 0xc00
	s_cbranch_scc0 .LBB0_365
	v_readlane_b32 s6, v237, 29
	v_readlane_b32 s7, v237, 30
	s_sub_u32 s6, s6, s26
	s_subb_u32 s7, s7, s27
	v_lshl_add_u64 v[2:3], v[2:3], 0, s[6:7]
	s_mov_b32 s6, 0x7600000
	s_mov_b32 s7, 0
	v_lshl_add_u64 v[0:1], v[0:1], 0, s[6:7]
	s_movk_i32 s11, 0x2000
	s_lshl_b32 s10, s84, 3
	s_add_i32 s10, s10, s93
	s_add_i32 s10, s10, 0xfffffc00
	s_movk_i32 s4, 0x2000
	v_writelane_b32 v236, s4, 60
	s_branch .LBB0_359

; __device__ __forceinline__ int lane_id() { int l; asm volatile("v_mbcnt_lo_u32_b32 %0, -1, 0\n\tv_mbcnt_hi_u32_b32 %0, -1, %0" : "=v"(l)); return l; }
; #define CONV_WFO(lo_, hi_, w_, nw_) do { LAS float* scr_ = (LAS float*)(lds + wave * 16384); for (int r = (lo_) + (w_); r < (hi_); r += (nw_)) { const int nblk = 4096 / 32, kb = r / nblk, nb = r % nblk; \
;         p0_item(in_w_ffn_out, 4096, DFF, Wfo_t, nb * 32, nb * 32, kb * 64, nullptr, scr_, lane); } } while (0)
; __global__ void __launch_bounds__(NWAVES * 64, 2) mk_fwd(Args args) {
;     ...
;         const int lane = lane_id();
;         if (split && bx >= 192) CONV_WFO(I_FO_P2, I_FO, (bx - 192) * NWAVES + wave, 64 * NWAVES); }
.LBB0_1397:
	s_lshl_b32 s0, s84, 3
	s_add_i32 s4, s93, s0
	s_cmpk_gt_i32 s84, 0xbf
	v_readlane_b32 s2, v237, 53
	s_cselect_b64 s[0:1], -1, 0
	v_readlane_b32 s3, v237, 54
	s_and_b64 s[2:3], s[0:1], s[2:3]
	s_add_i32 s1, s4, 0x600
	s_cmpk_lt_i32 s1, 0x5600
	s_cselect_b64 s[4:5], -1, 0
	s_and_b64 s[2:3], s[2:3], s[4:5]
	s_movk_i32 s0, 0x5600
	s_andn2_b64 vcc, exec, s[2:3]
	s_waitcnt lgkmcnt(0)
	v_mbcnt_lo_u32_b32 v2, -1, 0
	v_mbcnt_hi_u32_b32 v2, -1, v2
	s_cbranch_vccnz .LBB0_1406
	v_and_b32_e32 v0, 7, v2
	v_lshlrev_b32_e32 v4, 4, v0
	v_mov_b32_e32 v5, 0
	s_lshl_b32 s4, s93, 14
	v_ashrrev_i32_e32 v21, 3, v2
	v_mul_u32_u24_e32 v3, 0x420, v0
	v_lshl_add_u64 v[0:1], s[78:79], 0, v[4:5]
	s_mov_b64 s[2:3], 0x15b00000
	s_add_i32 s6, s4, 0
	v_ashrrev_i32_e32 v20, 5, v2
	v_lshl_add_u64 v[0:1], v[0:1], 0, s[2:3]
	v_lshlrev_b32_e32 v4, 2, v21
	s_movk_i32 s2, 0x84
	v_add3_u32 v22, s6, v3, v4
	v_mul_lo_u32 v3, v20, s2
	v_lshlrev_b32_e32 v2, 2, v2
	v_add_u32_e32 v3, s4, v3
	v_and_b32_e32 v4, 0x7c, v2
	s_mov_b32 s5, 0
	v_add3_u32 v23, v3, v4, 0
	v_lshl_add_u64 v[2:3], s[46:47], 0, v[4:5]
	v_add_u32_e32 v24, 14, v20
	v_add_u32_e32 v25, 12, v20
	v_add_u32_e32 v26, 10, v20
	v_add_u32_e32 v27, 8, v20
	v_add_u32_e32 v28, 6, v20
	v_add_u32_e32 v29, 4, v20
	v_add_u32_e32 v30, 2, v20
	s_branch .LBB0_1400
